# MIX seam XCD-local: attention units assigned by token range, MIX-done counter awaited at the OUT seam (H overlay guard)
# speedup vs baseline: 1.0136x; 1.0136x over previous
; #define LAS __attribute__((address_space(3)))
; __device__ __forceinline__ void attn_unit(LAS unsigned char* lds, int b, int h, int blk, const bf16_t* Q, const bf16_t* Kb, const bf16_t* Vt1, const bf16_t* Vt4, const bf16_t* Vt16,
;                                           bf16_t* MIX, i64* ssq_a, int wid, int lane_in) {
;     int lane = lane_in; asm volatile("" : "+v"(lane));
;     LAS float* Oacc = (LAS float*)lds; LAS float* Ml = Oacc + ABLK * OP;
;     const int qi = lane & 15, kq = lane >> 4, T0 = blk * ABLK;
;     const size_t tb = (size_t)b * SEQ; const size_t bhb = (size_t)(b * 8 + h) * (SEQ * 64);
; __global__ void __launch_bounds__(NWAVES * 64, 2) fwd_kernel(Args a) {
;     ...
;                   for (int u = cu; u < 256; u += G) { const int j = u >> 3, bh = (u & 7) * 2 + (j >> 4), blk = j & 15;
;                     attn_unit(lds, bh >> 3, bh & 7, blk, (const bf16_t*)(ws + WS_Q), (const bf16_t*)(ws + WS_K), (const bf16_t*)(ws + WS_VT1), (const bf16_t*)(ws + WS_VT4), (const bf16_t*)(ws + WS_VT16),
;                               (bf16_t*)(ws + WS_MIX), st + 2 * MTOK, wave, lane);
.LBB0_1081:
	s_bfe_u32 s4, s17, 0x10002
	v_mov_b32_e32 v136, v212
	s_lshl_b32 s4, s4, 3
	s_bfe_u32 s5, s17, 0x30003
	s_add_i32 s30, s4, s5
	v_and_b32_e32 v2, -16, v136
	v_ashrrev_i32_e32 v3, 31, v2
	s_and_b32 s22, s17, 3
	s_lshl_b32 s22, s22, 2
	s_bfe_u32 s31, s17, 0x20006
	s_add_i32 s22, s22, s31
	s_ashr_i32 s31, s30, 31
	v_lshlrev_b64 v[4:5], 1, v[2:3]
	v_lshlrev_b32_e32 v0, 1, v136
	v_and_b32_e32 v3, 3, v136
	s_lshl_b32 s18, s22, 9
	s_lshl_b64 s[4:5], s[30:31], 20
	v_and_or_b32 v139, v0, 24, v3
	v_ashrrev_i32_e32 v0, 1, v136
	v_and_b32_e32 v3, 64, v238
	s_add_u32 s20, s6, s4
	v_and_b32_e32 v140, -8, v0
	v_xor_b32_e32 v0, 16, v238
	v_add_u32_e32 v137, 64, v3
	s_addc_u32 s21, s7, s5
	v_cmp_lt_i32_e32 vcc, v0, v137
	v_lshl_add_u64 v[122:123], s[20:21], 0, v[4:5]
	s_add_u32 s20, s8, s4
	v_cndmask_b32_e32 v0, v238, v0, vcc
	s_addc_u32 s21, s9, s5
	v_lshlrev_b32_e32 v141, 2, v0
	v_xor_b32_e32 v0, 32, v238
	v_lshl_add_u64 v[124:125], s[20:21], 0, v[4:5]
	v_cmp_lt_i32_e32 vcc, v0, v137
	s_lshl_b32 s19, s22, 5
	s_lshl_b32 s20, s22, 7
	v_and_b32_e32 v138, 15, v136
	v_cndmask_b32_e32 v0, v238, v0, vcc
	s_add_u32 s4, s28, s4
	v_lshlrev_b32_e32 v142, 2, v0
	s_addc_u32 s5, s29, s5
	v_lshlrev_b32_e32 v0, 4, v138
	s_mov_b32 s43, 0
	v_add_u32_e32 v143, 0, v2
	v_cmp_gt_u32_e64 s[46:47], 16, v136
	v_or_b32_e32 v144, 4, v139
	v_or_b32_e32 v145, 32, v139
	v_or_b32_e32 v146, 36, v139
	v_or_b32_e32 v147, 64, v139
	v_or_b32_e32 v148, 0x44, v139
	v_or_b32_e32 v149, 0x60, v139
	v_or_b32_e32 v150, 0x64, v139
	v_or_b32_e32 v151, 0x80, v139
	v_or_b32_e32 v152, 0x84, v139
	v_or_b32_e32 v153, 0x80, v138
	v_or_b32_e32 v154, 16, v138
	v_or_b32_e32 v155, 0x90, v138
	v_lshl_add_u64 v[126:127], s[4:5], 0, v[0:1]
	s_mov_b32 s21, 0
	s_branch .LBB0_1083

; __device__ __forceinline__ unsigned xb_ld(unsigned* p)              { return __hip_atomic_load(p, __ATOMIC_RELAXED, __HIP_MEMORY_SCOPE_AGENT); }
; __device__ __forceinline__ unsigned xb_add(unsigned* p, unsigned v) { return __hip_atomic_fetch_add(p, v, __ATOMIC_RELAXED, __HIP_MEMORY_SCOPE_AGENT); }
; #define XB_SPIN(cond, bar) do { unsigned _sp = 0; while (cond) { __builtin_amdgcn_s_sleep(8); \
;     if ((++_sp & 255u) == 0u) { if (xb_ld(&(bar)[XB_TMO])) break; if (_sp > XB_SPIN_CAP) { atomicAdd(&(bar)[XB_TMO], 1u); break; } } } } while (0)
; #define SEAM(k) do { if ((k) + 1 < hi) { if ((k) == 0) grid.sync(); else { xcd_barrier(bar); if (DUP & 4) xcd_barrier(bar); } } } while (0)
; #define SEAM(k) do { } while (0)
; __device__ __forceinline__ void xcd_barrier(const XcdBarrier& b) {
;     asm volatile("s_waitcnt vmcnt(0)" ::: "memory");
;     __syncthreads();
;     if (threadIdx.x == 0) {
;         unsigned* bar = b.bar;
;         __builtin_amdgcn_s_waitcnt(0);
;         unsigned nloc = b.st[0], nx = b.st[1];
;         if (nloc == 0u) { xcd_barrier_complete(bar, b.x, nloc, nx); b.st[0] = nloc; b.st[1] = nx; }
;         const unsigned old = xb_add(&bar[XB_XSUB(b.x)], 1u);
;         const unsigned gen = old / nloc;
;         if (old + 1u == (gen + 1u) * nloc) {
;             __builtin_amdgcn_fence(__ATOMIC_RELEASE, "agent");
;             asm volatile("s_waitcnt vmcnt(0)" ::: "memory");
;             const unsigned og = xb_add(&bar[XB_TOP], 1u);
;             const unsigned tg = og / nx;
;             if (og + 1u == (tg + 1u) * nx) xb_add(&bar[XB_TOPGEN], 1u);
;             else XB_SPIN(xb_ld(&bar[XB_TOPGEN]) == tg, bar);
;             __builtin_amdgcn_fence(__ATOMIC_ACQUIRE, "agent");
;             xb_add(&bar[XB_XGEN(b.x)], 1u);
;             asm volatile("s_waitcnt vmcnt(0)" ::: "memory");
;         } else {
;             XB_SPIN(xb_ld(&bar[XB_XGEN(b.x)]) == gen, bar);
;             __builtin_amdgcn_fence(__ATOMIC_ACQUIRE, "agent");
;             asm volatile("s_waitcnt vmcnt(0)" ::: "memory");
;         }
;     }
;     __syncthreads();
; }
; __global__ void __launch_bounds__(NWAVES * 64, 2) fwd_kernel(Args a) {
;     ...
;                 SEAM(pb + 3);
.LBB0_1148:
	v_mov_b32_e32 v14, 0x23084
	ds_read_b32 v14, v14
	s_waitcnt lgkmcnt(0)
	v_readfirstlane_b32 s5, v14
	s_nop 3
	s_cmp_eq_u32 s5, 0
	s_cbranch_scc1 .Lmx_full
	v_readlane_b32 s4, v253, 44
	v_readlane_b32 s5, v253, 45
	v_readlane_b32 s8, v252, 34
	v_readlane_b32 s9, v252, 35
	v_mov_b32_e32 v14, 0x2308c
	ds_add_rtn_u32 v13, v14, v3
	v_mov_b32_e32 v11, 1
	s_nop 1
	global_atomic_add v1, v11, s[8:9] offset:-192
	global_atomic_add v1, v11, s[4:5] offset:128
	s_waitcnt lgkmcnt(0)
	v_add_u32_e32 v13, v13, v3
	s_mov_b32 s6, 0
.Lmx_poll:
	global_load_dword v12, v1, s[4:5] offset:128 sc1
	s_waitcnt vmcnt(0)
	v_cmp_ge_u32_e32 vcc, v12, v13
	s_cbranch_vccnz .Lmx_done
	s_add_i32 s6, s6, 1
	s_cmp_lt_u32 s6, 0x2000
	s_cbranch_scc0 .Lmx_done
	s_sleep 2
	s_branch .Lmx_poll

; __device__ __forceinline__ unsigned xb_ld(unsigned* p)              { return __hip_atomic_load(p, __ATOMIC_RELAXED, __HIP_MEMORY_SCOPE_AGENT); }
; __device__ __forceinline__ unsigned xb_add(unsigned* p, unsigned v) { return __hip_atomic_fetch_add(p, v, __ATOMIC_RELAXED, __HIP_MEMORY_SCOPE_AGENT); }
; #define XB_SPIN(cond, bar) do { unsigned _sp = 0; while (cond) { __builtin_amdgcn_s_sleep(8); \
;     if ((++_sp & 255u) == 0u) { if (xb_ld(&(bar)[XB_TMO])) break; if (_sp > XB_SPIN_CAP) { atomicAdd(&(bar)[XB_TMO], 1u); break; } } } } while (0)
; #define SEAM(k) do { if ((k) + 1 < hi) { if ((k) == 0) grid.sync(); else { xcd_barrier(bar); if (DUP & 4) xcd_barrier(bar); } } } while (0)
; #define SEAM(k) do { } while (0)
; __device__ __forceinline__ void xcd_barrier(const XcdBarrier& b) {
;     asm volatile("s_waitcnt vmcnt(0)" ::: "memory");
;     __syncthreads();
;     if (threadIdx.x == 0) {
;         unsigned* bar = b.bar;
;         __builtin_amdgcn_s_waitcnt(0);
;         unsigned nloc = b.st[0], nx = b.st[1];
;         if (nloc == 0u) { xcd_barrier_complete(bar, b.x, nloc, nx); b.st[0] = nloc; b.st[1] = nx; }
;         const unsigned old = xb_add(&bar[XB_XSUB(b.x)], 1u);
;         const unsigned gen = old / nloc;
;         if (old + 1u == (gen + 1u) * nloc) {
;             __builtin_amdgcn_fence(__ATOMIC_RELEASE, "agent");
;             asm volatile("s_waitcnt vmcnt(0)" ::: "memory");
;             const unsigned og = xb_add(&bar[XB_TOP], 1u);
;             const unsigned tg = og / nx;
;             if (og + 1u == (tg + 1u) * nx) xb_add(&bar[XB_TOPGEN], 1u);
;             else XB_SPIN(xb_ld(&bar[XB_TOPGEN]) == tg, bar);
;             __builtin_amdgcn_fence(__ATOMIC_ACQUIRE, "agent");
;             xb_add(&bar[XB_XGEN(b.x)], 1u);
;             asm volatile("s_waitcnt vmcnt(0)" ::: "memory");
;         } else {
;             XB_SPIN(xb_ld(&bar[XB_XGEN(b.x)]) == gen, bar);
;             __builtin_amdgcn_fence(__ATOMIC_ACQUIRE, "agent");
;             asm volatile("s_waitcnt vmcnt(0)" ::: "memory");
;         }
;     }
;     __syncthreads();
; }
; __global__ void __launch_bounds__(NWAVES * 64, 2) fwd_kernel(Args a) {
;     ...
;                 SEAM(pb + 4);
.LBB0_1241:
	v_mov_b32_e32 v14, 0x23084
	ds_read_b32 v14, v14
	s_waitcnt lgkmcnt(0)
	v_readfirstlane_b32 s5, v14
	s_nop 3
	s_cmp_eq_u32 s5, 0
	s_cbranch_scc1 .Lout_full
	v_readlane_b32 s4, v252, 34
	v_readlane_b32 s5, v252, 35
	s_and_b32 s6, s2, 7
	s_lshl_b32 s6, s6, 3
	s_bfe_u32 s7, s2, 0x30003
	s_or_b32 s6, s6, s7
	s_lshl_b32 s6, s6, 5
	s_addk_i32 s6, 0x3600
	s_add_u32 s4, s4, s6
	s_addc_u32 s5, s5, 0
	v_mov_b32_e32 v14, 0x23088
	v_mov_b32_e32 v12, 4
	ds_add_rtn_u32 v13, v14, v12
	v_mov_b32_e32 v11, 1
	s_nop 1
	global_atomic_add v1, v11, s[4:5]
	buffer_inv sc1
	s_waitcnt lgkmcnt(0)
	v_add_u32_e32 v13, 4, v13
	s_mov_b32 s8, 0
	v_readlane_b32 s6, v252, 34
	v_readlane_b32 s7, v252, 35
	v_mov_b32_e32 v14, 0x230a0
	v_mov_b32_e32 v10, 0x100
	ds_add_rtn_u32 v10, v14, v10
	s_waitcnt lgkmcnt(0)
	v_add_u32_e32 v10, 0x100, v10
.Lout_lpoll:
	global_load_dword v12, v1, s[4:5] sc1
	global_load_dword v9, v1, s[6:7] offset:-192 sc1
	s_waitcnt vmcnt(0)
	v_cmp_ge_u32_e32 vcc, v12, v13
	v_cmp_ge_u32_e64 s[30:31], v9, v10
	s_nop 1
	s_and_b64 vcc, vcc, s[30:31]
	s_cbranch_vccnz .Lout_ldone
	s_add_i32 s8, s8, 1
	s_cmp_lt_u32 s8, 0x2000
	s_cbranch_scc0 .Lout_ldone
	s_sleep 2
	s_branch .Lout_lpoll
